# PR1: s_setprio 2 for the critical-role waves of the wave-specialised prologue phases (streaming waves 4-7 in phase 0, weight-product waves 0-3 in phase 1)
# baseline (speedup 1.0000x reference)
; __device__ void p0_xconv(const Args& a) {
;     f16* XH = (f16*)(a.ws + WS_XH); float* SS = (float*)(a.ws + WS_SS);
;     int tid_ = threadIdx.x; asm volatile("" : "+v"(tid_));
;     const int lane = tid_ & 63, wv = tid_ >> 6;
;     const int nwv = (int)gridDim.x * 8;
;     for (int row0 = (int)blockIdx.x * 8 + wv; row0 < MROWS; row0 += 4 * nwv) {
;     ...
;                 for (int o = 1; o < 64; o <<= 1) ss += __shfl_xor(ss, o);
;                 if (lane < 16) SS[(size_t)row * 16 + lane] = (lane == 0) ? ss : 0.f;
.Lws_x:
	s_setprio 2
	v_writelane_b32 v255, s14, 10
	v_writelane_b32 v255, s15, 11
	v_writelane_b32 v255, s20, 12
	v_writelane_b32 v255, s21, 13
	v_writelane_b32 v255, s22, 14
	v_writelane_b32 v255, s23, 15
	v_mov_b32_e32 v1, v0
	s_mov_b32 s3, 0x8000
	v_ashrrev_i32_e32 v2, 6, v1
	v_lshl_add_u32 v78, s2, 2, v2
	v_add_u32_e32 v78, -4, v78
	v_cmp_gt_i32_e32 vcc, s3, v78
	s_and_saveexec_b64 s[20:21], vcc
	s_cbranch_execz .Lxc_111
	v_and_b32_e32 v1, 63, v1
	v_mov_b32_e32 v67, 0
	v_lshlrev_b32_e32 v66, 2, v1
	v_lshlrev_b32_e32 v2, 3, v1
	v_mov_b32_e32 v3, v67
	s_movk_i32 s36, 0x80
	v_lshl_add_u64 v[68:69], s[40:41], 0, v[2:3]
	v_lshl_add_u64 v[2:3], s[40:41], 0, v[66:67]
	s_mov_b64 s[4:5], 0x1f800000
	v_cmp_gt_u32_e32 vcc, 16, v1
	v_lshl_add_u64 v[70:71], v[2:3], 0, s[4:5]
	v_cmp_eq_u32_e64 s[4:5], 0, v1
	v_mbcnt_lo_u32_b32 v1, -1, 0
	v_mbcnt_hi_u32_b32 v2, -1, v1
	v_and_b32_e32 v1, 64, v2
	v_add_u32_e32 v3, 64, v1
	v_xor_b32_e32 v1, 1, v2
	v_cmp_lt_i32_e64 s[6:7], v1, v3
	v_xor_b32_e32 v4, 2, v2
	s_waitcnt lgkmcnt(0)
	s_lshl_b32 s9, s36, 3
	v_cndmask_b32_e64 v1, v2, v1, s[6:7]
	v_cmp_lt_i32_e64 s[6:7], v4, v3
	s_add_i32 s44, s9, s9
	v_lshlrev_b32_e32 v1, 2, v1
	v_cndmask_b32_e64 v4, v2, v4, s[6:7]
	v_lshlrev_b32_e32 v80, 2, v4
	v_xor_b32_e32 v4, 4, v2
	v_cmp_lt_i32_e64 s[6:7], v4, v3
	s_lshl_b32 s33, s36, 4
	s_mul_i32 s36, s36, 24
	v_cndmask_b32_e64 v4, v2, v4, s[6:7]
	v_lshlrev_b32_e32 v81, 2, v4
	v_xor_b32_e32 v4, 8, v2
	v_cmp_lt_i32_e64 s[6:7], v4, v3
	s_mov_b64 s[22:23], 0
	s_movk_i32 s37, 0x4000
	v_cndmask_b32_e64 v4, v2, v4, s[6:7]
	v_lshlrev_b32_e32 v82, 2, v4
	v_xor_b32_e32 v4, 16, v2
	v_cmp_lt_i32_e64 s[6:7], v4, v3
	v_mov_b32_e32 v85, s19
	v_mov_b32_e32 v86, s17
	v_cndmask_b32_e64 v4, v2, v4, s[6:7]
	v_lshlrev_b32_e32 v83, 2, v4
	v_xor_b32_e32 v4, 32, v2
	v_cmp_lt_i32_e64 s[6:7], v4, v3
	v_mov_b32_e32 v87, s18
	v_mov_b32_e32 v88, s16
	v_cndmask_b32_e64 v2, v2, v4, s[6:7]
	v_lshlrev_b32_e32 v84, 2, v2
	v_lshlrev_b32_e32 v66, 2, v66
	s_add_i32 s44, s44, s9
	s_mov_b32 s45, 0x7fff
	s_branch .Lxc_94

; __device__ void p0_xconv(const Args& a) {
;     ...
;     }
; }
.Lxc_111:
	s_or_b64 exec, exec, s[20:21]
	v_readlane_b32 s14, v255, 10
	v_readlane_b32 s15, v255, 11
	v_readlane_b32 s20, v255, 12
	v_readlane_b32 s21, v255, 13
	v_readlane_b32 s22, v255, 14
	v_readlane_b32 s23, v255, 15
	s_nop 3
	s_setprio 0
	s_branch .LBB0_37

; #define LAS __attribute__((address_space(3)))
; __device__ void p_weights_prod(const Args& a, LAS unsigned char* lds) {
;     ...
;     LAS float* wt = (LAS float*)lds;
;     LAS float* mmt = (LAS float*)(lds + 16384);
;     for (int u = blockIdx.x; u < 256; u += gridDim.x) {
;         const int l = u >> 7, g = (u >> 5) & 3, kblk = u & 31, pn = 7 + g;
;         __syncthreads();
;         {
;             const int rr = tid >> 4, c8 = (tid & 15) * 8;
;             const float* src = a.w_in + (size_t)l * DM * INW + (size_t)(kblk * 32 + rr) * INW + 1280 + g * 128 + c8;
;             const f32x4* msrc = (const f32x4*)(MM + (size_t)(l * 4 + g) * 128 * 256) + tid;
;             f32x4 mreg[16];
; #pragma unroll
;             for (int j = 0; j < 16; ++j) mreg[j] = msrc[j * NTHREADS];
;             *(LAS f32x4*)(wt + rr * 128 + c8) = *(const f32x4*)src; *(LAS f32x4*)(wt + rr * 128 + c8 + 4) = *(const f32x4*)(src + 4);
.LBB0_86:
.LBB0_87:
	v_readfirstlane_b32 s100, v0
	s_nop 3
	s_cmp_ge_u32 s100, 0x100
	s_cbranch_scc1 .Lpw_x
	s_setprio 2
	v_mov_b32_e32 v8, v0
	v_lshlrev_b32_e32 v10, 4, v8
	s_load_dword s9, s[0:1], 0x60
	s_add_u32 s6, s40, 0x1fb00000
	v_lshlrev_b32_e32 v1, 1, v8
	v_and_b32_e32 v2, 0x90, v10
	s_movk_i32 s3, 0x6c
	v_lshlrev_b32_e32 v3, 3, v8
	v_ashrrev_i32_e32 v9, 31, v8
	s_addc_u32 s7, s41, 0
	v_and_or_b32 v2, v1, s3, v2
	v_ashrrev_i32_e32 v11, 6, v8
	v_ashrrev_i32_e32 v1, 4, v8
	v_and_b32_e32 v4, 0x78, v3
	v_lshl_add_u64 v[6:7], v[8:9], 4, s[40:41]
	s_mov_b64 s[4:5], 0x20a00000
	v_and_b32_e32 v8, 63, v8
	v_lshl_add_u64 v[6:7], v[6:7], 0, s[4:5]
	v_lshlrev_b32_e32 v3, 9, v1
	v_lshlrev_b32_e32 v9, 2, v4
	v_add_u32_e32 v24, 0, v10
	s_add_u32 s4, s0, 0x60
	v_lshl_add_u32 v8, v8, 4, 0
	v_mov_b32_e32 v5, 0
	s_mov_b32 s11, 0
	v_add3_u32 v3, 0, v3, v9
	s_movk_i32 s3, 0x4000
	v_add_u32_e32 v25, 0x4000, v24
	v_lshl_add_u32 v26, v11, 11, 0
	v_lshlrev_b32_e32 v27, 2, v11
	s_addc_u32 s5, s1, 0
	s_mov_b32 s14, 0x14000
	v_add_u32_e32 v28, 0x14000, v24
	s_mov_b32 s15, 0x16000
	v_add_u32_e32 v29, 0x16000, v24
	s_mov_b32 s33, 0x18000
	v_add_u32_e32 v30, 0x18000, v24
	s_mov_b32 s34, 0x1a000
	v_add_u32_e32 v31, 0x1a000, v24
	s_mov_b32 s35, 0x1c000
	v_add_u32_e32 v32, 0x1c000, v24
	s_mov_b32 s36, 0x1e000
	v_add_u32_e32 v33, 0x1e000, v24
	v_add_u32_e32 v34, 0x20000, v24
	v_add_u32_e32 v35, 0x22000, v24
	v_add_u32_e32 v36, 0x4000, v8
	s_movk_i32 s37, 0x2400
	s_movk_i32 s44, 0x2000
	s_movk_i32 s45, 0x6000
	s_mov_b32 s46, 0x8000
	s_mov_b32 s47, 0xa000
	s_mov_b32 s48, 0xc000
	s_mov_b32 s49, 0xe000
	s_mov_b32 s50, 0x10000
	s_mov_b32 s51, 0x12000
	v_lshlrev_b32_e32 v4, 2, v4
	s_mov_b64 s[12:13], 0x1400
	s_movk_i32 s52, 0x1000
	s_mov_b32 s53, s2
	s_ashr_i32 s55, s53, 7
	s_bfe_u32 s54, s53, 0x20005
	s_mul_i32 s56, s55, 0x900000
	s_mul_hi_i32 s10, s55, 0x900000
	s_add_u32 s58, s22, s56
	s_addc_u32 s59, s23, s10
	s_lshl_b32 s10, s53, 5
	s_and_b32 s56, s10, 0x3e0
	v_add_u32_e32 v10, s56, v1
	v_mov_b64_e32 v[8:9], s[58:59]
	v_mad_i64_i32 v[8:9], s[58:59], v10, s37, v[8:9]
	s_lshl_b32 s10, s54, 9
	v_lshl_add_u64 v[8:9], v[8:9], 0, s[10:11]
	s_lshl_b32 s10, s55, 2
	s_or_b32 s58, s10, s54
	v_lshl_add_u64 v[8:9], v[8:9], 0, v[4:5]
	s_ashr_i32 s59, s58, 31
	v_add_co_u32_e32 v10, vcc, s52, v8
	s_lshl_b64 s[58:59], s[58:59], 17
	s_nop 0
	v_addc_co_u32_e32 v11, vcc, 0, v9, vcc
	v_lshl_add_u64 v[86:87], v[6:7], 0, s[58:59]
	v_add_co_u32_e32 v20, vcc, s44, v86
	v_lshl_add_u64 v[12:13], v[8:9], 0, s[12:13]
	s_nop 0
	v_addc_co_u32_e32 v21, vcc, 0, v87, vcc
	v_add_co_u32_e32 v38, vcc, s3, v86
	s_waitcnt lgkmcnt(0)
	s_nop 0
	v_addc_co_u32_e32 v39, vcc, 0, v87, vcc
	v_add_co_u32_e32 v42, vcc, s45, v86
	s_barrier
	s_nop 0
	v_addc_co_u32_e32 v43, vcc, 0, v87, vcc
	v_add_co_u32_e32 v46, vcc, s46, v86
	s_nop 1
	v_addc_co_u32_e32 v47, vcc, 0, v87, vcc
	v_add_co_u32_e32 v50, vcc, s47, v86
	global_load_dwordx4 v[8:11], v[10:11], off offset:1024
	s_nop 0
	global_load_dwordx4 v[12:15], v[12:13], off offset:16
	v_addc_co_u32_e32 v51, vcc, 0, v87, vcc
	v_add_co_u32_e32 v54, vcc, s48, v86
	global_load_dwordx4 v[16:19], v[86:87], off
	s_nop 0
	global_load_dwordx4 v[20:23], v[20:21], off
	v_addc_co_u32_e32 v55, vcc, 0, v87, vcc
	v_add_co_u32_e32 v58, vcc, s49, v86
	global_load_dwordx4 v[38:41], v[38:39], off
	s_nop 0
	global_load_dwordx4 v[42:45], v[42:43], off
	v_addc_co_u32_e32 v59, vcc, 0, v87, vcc
	v_add_co_u32_e32 v62, vcc, s50, v86
	global_load_dwordx4 v[46:49], v[46:47], off
	s_nop 0
	global_load_dwordx4 v[50:53], v[50:51], off
	v_addc_co_u32_e32 v63, vcc, 0, v87, vcc
	v_add_co_u32_e32 v66, vcc, s51, v86
	s_mov_b32 s10, -4
	s_nop 0
	v_addc_co_u32_e32 v67, vcc, 0, v87, vcc
	v_add_co_u32_e32 v70, vcc, s14, v86
	v_mov_b32_e32 v37, v26
	s_nop 0
	v_addc_co_u32_e32 v71, vcc, 0, v87, vcc
	v_add_co_u32_e32 v74, vcc, s15, v86
	s_nop 1
	v_addc_co_u32_e32 v75, vcc, 0, v87, vcc
	v_add_co_u32_e32 v78, vcc, s33, v86
	global_load_dwordx4 v[54:57], v[54:55], off
	s_nop 0
	global_load_dwordx4 v[58:61], v[58:59], off
	s_nop 0
	global_load_dwordx4 v[62:65], v[62:63], off
	s_nop 0
	global_load_dwordx4 v[66:69], v[66:67], off
	s_nop 0
	global_load_dwordx4 v[70:73], v[70:71], off
	s_nop 0
	global_load_dwordx4 v[74:77], v[74:75], off
	v_addc_co_u32_e32 v79, vcc, 0, v87, vcc
	v_add_co_u32_e32 v82, vcc, s34, v86
	s_nop 1
	v_addc_co_u32_e32 v83, vcc, 0, v87, vcc
	v_add_co_u32_e32 v88, vcc, s35, v86
	global_load_dwordx4 v[78:81], v[78:79], off
	s_nop 0
	global_load_dwordx4 v[82:85], v[82:83], off
	v_addc_co_u32_e32 v89, vcc, 0, v87, vcc
	v_add_co_u32_e32 v90, vcc, s36, v86
	s_nop 1
	v_addc_co_u32_e32 v91, vcc, 0, v87, vcc
	global_load_dwordx4 v[86:89], v[88:89], off
	s_nop 0
	global_load_dwordx4 v[90:93], v[90:91], off
	v_add_u32_e32 v108, 0x100, v0
	v_lshlrev_b32_e32 v110, 4, v108
	s_load_dword s9, s[0:1], 0x60
	s_add_u32 s6, s40, 0x1fb00000
	v_lshlrev_b32_e32 v101, 1, v108
	v_and_b32_e32 v102, 0x90, v110
	s_movk_i32 s3, 0x6c
	v_lshlrev_b32_e32 v103, 3, v108
	v_ashrrev_i32_e32 v109, 31, v108
	s_addc_u32 s7, s41, 0
	v_and_or_b32 v102, v101, s3, v102
	v_ashrrev_i32_e32 v111, 6, v108
	v_ashrrev_i32_e32 v101, 4, v108
	v_and_b32_e32 v104, 0x78, v103
	v_lshl_add_u64 v[106:107], v[108:109], 4, s[40:41]
	s_mov_b64 s[4:5], 0x20a00000
	v_and_b32_e32 v108, 63, v108
	v_lshl_add_u64 v[106:107], v[106:107], 0, s[4:5]
	v_lshlrev_b32_e32 v103, 9, v101
	v_lshlrev_b32_e32 v109, 2, v104
	v_add_u32_e32 v124, 0, v110
	s_add_u32 s4, s0, 0x60
	v_lshl_add_u32 v108, v108, 4, 0
	v_mov_b32_e32 v105, 0
	s_mov_b32 s11, 0
	v_add3_u32 v103, 0, v103, v109
	s_movk_i32 s3, 0x4000
	v_add_u32_e32 v125, 0x4000, v124
	v_lshl_add_u32 v126, v111, 11, 0
; #define LAS __attribute__((address_space(3)))
; __device__ void p_weights_prod(const Args& a, LAS unsigned char* lds) {
;     ...
;             const int rr = tid >> 4, c8 = (tid & 15) * 8;
;             const float* src = a.w_in + (size_t)l * DM * INW + (size_t)(kblk * 32 + rr) * INW + 1280 + g * 128 + c8;
;             const f32x4* msrc = (const f32x4*)(MM + (size_t)(l * 4 + g) * 128 * 256) + tid;
;             f32x4 mreg[16];
; #pragma unroll
;             for (int j = 0; j < 16; ++j) mreg[j] = msrc[j * NTHREADS];
;             *(LAS f32x4*)(wt + rr * 128 + c8) = *(const f32x4*)src; *(LAS f32x4*)(wt + rr * 128 + c8 + 4) = *(const f32x4*)(src + 4);
; #pragma unroll
;             for (int j = 0; j < 16; ++j) ((LAS f32x4*)mmt)[tid + j * NTHREADS] = mreg[j];
;         }
;         __syncthreads();
;         f32x4 acc[4];
; #pragma unroll
;         for (int r2 = 0; r2 < 4; ++r2) acc[r2] = (f32x4){0.f, 0.f, 0.f, 0.f};
	v_lshlrev_b32_e32 v127, 2, v111
	s_addc_u32 s5, s1, 0
	s_mov_b32 s14, 0x14000
	v_add_u32_e32 v128, 0x14000, v124
	s_mov_b32 s15, 0x16000
	v_add_u32_e32 v129, 0x16000, v124
	s_mov_b32 s33, 0x18000
	v_add_u32_e32 v130, 0x18000, v124
	s_mov_b32 s34, 0x1a000
	v_add_u32_e32 v131, 0x1a000, v124
	s_mov_b32 s35, 0x1c000
	v_add_u32_e32 v132, 0x1c000, v124
	s_mov_b32 s36, 0x1e000
	v_add_u32_e32 v133, 0x1e000, v124
	v_add_u32_e32 v134, 0x20000, v124
	v_add_u32_e32 v135, 0x22000, v124
	v_add_u32_e32 v136, 0x4000, v108
	s_movk_i32 s37, 0x2400
	s_movk_i32 s44, 0x2000
	s_movk_i32 s45, 0x6000
	s_mov_b32 s46, 0x8000
	s_mov_b32 s47, 0xa000
	s_mov_b32 s48, 0xc000
	s_mov_b32 s49, 0xe000
	s_mov_b32 s50, 0x10000
	s_mov_b32 s51, 0x12000
	v_lshlrev_b32_e32 v104, 2, v104
	s_mov_b64 s[12:13], 0x1400
	s_movk_i32 s52, 0x1000
	s_mov_b32 s53, s2
	s_ashr_i32 s55, s53, 7
	s_bfe_u32 s54, s53, 0x20005
	s_mul_i32 s56, s55, 0x900000
	s_mul_hi_i32 s10, s55, 0x900000
	s_add_u32 s58, s22, s56
	s_addc_u32 s59, s23, s10
	s_lshl_b32 s10, s53, 5
	s_and_b32 s56, s10, 0x3e0
	v_add_u32_e32 v110, s56, v101
	v_mov_b64_e32 v[108:109], s[58:59]
	v_mad_i64_i32 v[108:109], s[58:59], v110, s37, v[108:109]
	s_lshl_b32 s10, s54, 9
	v_lshl_add_u64 v[108:109], v[108:109], 0, s[10:11]
	s_lshl_b32 s10, s55, 2
	s_or_b32 s58, s10, s54
	v_lshl_add_u64 v[108:109], v[108:109], 0, v[104:105]
	s_ashr_i32 s59, s58, 31
	v_add_co_u32_e32 v110, vcc, s52, v108
	s_lshl_b64 s[58:59], s[58:59], 17
	s_nop 0
	v_addc_co_u32_e32 v111, vcc, 0, v109, vcc
	v_lshl_add_u64 v[186:187], v[106:107], 0, s[58:59]
	v_add_co_u32_e32 v120, vcc, s44, v186
	v_lshl_add_u64 v[112:113], v[108:109], 0, s[12:13]
	s_nop 0
	v_addc_co_u32_e32 v121, vcc, 0, v187, vcc
	v_add_co_u32_e32 v138, vcc, s3, v186
	s_waitcnt lgkmcnt(0)
	s_nop 0
	v_addc_co_u32_e32 v139, vcc, 0, v187, vcc
	v_add_co_u32_e32 v142, vcc, s45, v186
	s_nop 0
	v_addc_co_u32_e32 v143, vcc, 0, v187, vcc
	v_add_co_u32_e32 v146, vcc, s46, v186
	s_nop 1
	v_addc_co_u32_e32 v147, vcc, 0, v187, vcc
	v_add_co_u32_e32 v150, vcc, s47, v186
	global_load_dwordx4 v[108:111], v[110:111], off offset:1024
	s_nop 0
	global_load_dwordx4 v[112:115], v[112:113], off offset:16
	v_addc_co_u32_e32 v151, vcc, 0, v187, vcc
	v_add_co_u32_e32 v154, vcc, s48, v186
	global_load_dwordx4 v[116:119], v[186:187], off
	s_nop 0
	global_load_dwordx4 v[120:123], v[120:121], off
	v_addc_co_u32_e32 v155, vcc, 0, v187, vcc
	v_add_co_u32_e32 v158, vcc, s49, v186
	global_load_dwordx4 v[138:141], v[138:139], off
	s_nop 0
	global_load_dwordx4 v[142:145], v[142:143], off
	v_addc_co_u32_e32 v159, vcc, 0, v187, vcc
	v_add_co_u32_e32 v162, vcc, s50, v186
	global_load_dwordx4 v[146:149], v[146:147], off
	s_nop 0
	global_load_dwordx4 v[150:153], v[150:151], off
	v_addc_co_u32_e32 v163, vcc, 0, v187, vcc
	v_add_co_u32_e32 v166, vcc, s51, v186
	s_mov_b32 s10, -4
	s_nop 0
	v_addc_co_u32_e32 v167, vcc, 0, v187, vcc
	v_add_co_u32_e32 v170, vcc, s14, v186
	v_mov_b32_e32 v137, v126
	s_nop 0
	v_addc_co_u32_e32 v171, vcc, 0, v187, vcc
	v_add_co_u32_e32 v174, vcc, s15, v186
	s_nop 1
	v_addc_co_u32_e32 v175, vcc, 0, v187, vcc
	v_add_co_u32_e32 v178, vcc, s33, v186
	global_load_dwordx4 v[154:157], v[154:155], off
	s_nop 0
	global_load_dwordx4 v[158:161], v[158:159], off
	s_nop 0
	global_load_dwordx4 v[162:165], v[162:163], off
	s_nop 0
	global_load_dwordx4 v[166:169], v[166:167], off
	s_nop 0
	global_load_dwordx4 v[170:173], v[170:171], off
	s_nop 0
	global_load_dwordx4 v[174:177], v[174:175], off
	v_addc_co_u32_e32 v179, vcc, 0, v187, vcc
	v_add_co_u32_e32 v182, vcc, s34, v186
	s_nop 1
	v_addc_co_u32_e32 v183, vcc, 0, v187, vcc
	v_add_co_u32_e32 v188, vcc, s35, v186
	global_load_dwordx4 v[178:181], v[178:179], off
	s_nop 0
	global_load_dwordx4 v[182:185], v[182:183], off
	v_addc_co_u32_e32 v189, vcc, 0, v187, vcc
	v_add_co_u32_e32 v190, vcc, s36, v186
	s_nop 1
	v_addc_co_u32_e32 v191, vcc, 0, v187, vcc
	global_load_dwordx4 v[186:189], v[188:189], off
	s_nop 0
	global_load_dwordx4 v[190:193], v[190:191], off
	s_waitcnt vmcnt(0)
	ds_write_b128 v3, v[8:11]
	ds_write_b128 v3, v[12:15] offset:16
	ds_write_b128 v24, v[16:19] offset:16384
	ds_write_b128 v24, v[20:23] offset:24576
	ds_write_b128 v24, v[38:41] offset:32768
	ds_write_b128 v24, v[42:45] offset:40960
	ds_write_b128 v24, v[46:49] offset:49152
	ds_write_b128 v24, v[50:53] offset:57344
	ds_write_b128 v25, v[54:57] offset:49152
	ds_write_b128 v25, v[58:61] offset:57344
	ds_write_b128 v28, v[62:65]
	ds_write_b128 v29, v[66:69]
	ds_write_b128 v30, v[70:73]
	ds_write_b128 v31, v[74:77]
	ds_write_b128 v32, v[78:81]
	ds_write_b128 v33, v[82:85]
	ds_write_b128 v34, v[86:89]
	ds_write_b128 v35, v[90:93]
	v_mov_b32_e32 v38, v36
	v_mov_b32_e32 v10, 0
	v_mov_b32_e32 v11, v5
	v_mov_b32_e32 v8, 0
	v_mov_b32_e32 v9, v5
	v_mov_b32_e32 v22, 0
	v_mov_b32_e32 v23, v5
	v_mov_b32_e32 v20, 0
	v_mov_b32_e32 v21, v5
	v_mov_b32_e32 v14, 0
	v_mov_b32_e32 v15, v5
	v_mov_b32_e32 v12, 0
	v_mov_b32_e32 v13, v5
	v_mov_b32_e32 v18, 0
	v_mov_b32_e32 v19, v5
	v_mov_b32_e32 v16, 0
	v_mov_b32_e32 v17, v5
	s_waitcnt vmcnt(0)
	ds_write_b128 v103, v[108:111]
	ds_write_b128 v103, v[112:115] offset:16
	ds_write_b128 v124, v[116:119] offset:16384
	ds_write_b128 v124, v[120:123] offset:24576
	ds_write_b128 v124, v[138:141] offset:32768
	ds_write_b128 v124, v[142:145] offset:40960
	ds_write_b128 v124, v[146:149] offset:49152
	ds_write_b128 v124, v[150:153] offset:57344
	ds_write_b128 v125, v[154:157] offset:49152
	ds_write_b128 v125, v[158:161] offset:57344
	ds_write_b128 v128, v[162:165]
	ds_write_b128 v129, v[166:169]
	ds_write_b128 v130, v[170:173]
	ds_write_b128 v131, v[174:177]
	ds_write_b128 v132, v[178:181]
	ds_write_b128 v133, v[182:185]
	ds_write_b128 v134, v[186:189]
	ds_write_b128 v135, v[190:193]
	v_mov_b32_e32 v138, v136
	v_mov_b32_e32 v110, 0
	v_mov_b32_e32 v111, v105
	v_mov_b32_e32 v108, 0
	v_mov_b32_e32 v109, v105
	v_mov_b32_e32 v122, 0
	v_mov_b32_e32 v123, v105
	v_mov_b32_e32 v120, 0
	v_mov_b32_e32 v121, v105
	v_mov_b32_e32 v114, 0
	v_mov_b32_e32 v115, v105
	v_mov_b32_e32 v112, 0
	v_mov_b32_e32 v113, v105
	v_mov_b32_e32 v118, 0
	v_mov_b32_e32 v119, v105
	v_mov_b32_e32 v116, 0
	v_mov_b32_e32 v117, v105
	s_waitcnt lgkmcnt(0)
	s_barrier
; #define LAS __attribute__((address_space(3)))
; __device__ void p_weights_prod(const Args& a, LAS unsigned char* lds) {
;     ...
;         f32x4 acc[4];
; #pragma unroll
;         for (int r2 = 0; r2 < 4; ++r2) acc[r2] = (f32x4){0.f, 0.f, 0.f, 0.f};
; #pragma unroll 2
;         for (int c0 = 0; c0 < 128; c0 += 4) {
;             f32x4 w4[4], m4[4];
; #pragma unroll
;             for (int r2 = 0; r2 < 4; ++r2) w4[r2] = *(const LAS f32x4*)(wt + (4 * rq + r2) * 128 + c0);
; #pragma unroll
;             for (int cc = 0; cc < 4; ++cc) m4[cc] = *(const LAS f32x4*)(mmt + (c0 + cc) * 256 + lc0);
; #pragma unroll
;             for (int r2 = 0; r2 < 4; ++r2)
; #pragma unroll
;                 for (int cc = 0; cc < 4; ++cc) acc[r2] += m4[cc] * w4[r2][cc];
;         }
;         const int k0 = kblk * 32 + 4 * rq;
;         const f32x4 gn = *(const f32x4*)(a.norm_gain + l * DM + k0);
	v_mov_b32_e32 v8, v0
	v_lshlrev_b32_e32 v10, 4, v8
	s_load_dword s9, s[0:1], 0x60
	s_add_u32 s6, s40, 0x1fb00000
	v_lshlrev_b32_e32 v1, 1, v8
	v_and_b32_e32 v2, 0x90, v10
	s_movk_i32 s3, 0x6c
	v_lshlrev_b32_e32 v3, 3, v8
	v_ashrrev_i32_e32 v9, 31, v8
	s_addc_u32 s7, s41, 0
	v_and_or_b32 v2, v1, s3, v2
	v_ashrrev_i32_e32 v11, 6, v8
	v_ashrrev_i32_e32 v1, 4, v8
	v_and_b32_e32 v4, 0x78, v3
	v_lshl_add_u64 v[6:7], v[8:9], 4, s[40:41]
	s_mov_b64 s[4:5], 0x20a00000
	v_and_b32_e32 v8, 63, v8
	v_lshl_add_u64 v[6:7], v[6:7], 0, s[4:5]
	v_lshlrev_b32_e32 v3, 9, v1
	v_lshlrev_b32_e32 v9, 2, v4
	v_add_u32_e32 v24, 0, v10
	s_add_u32 s4, s0, 0x60
	v_lshl_add_u32 v8, v8, 4, 0
	v_mov_b32_e32 v5, 0
	s_mov_b32 s11, 0
	v_add3_u32 v3, 0, v3, v9
	s_movk_i32 s3, 0x4000
	v_add_u32_e32 v25, 0x4000, v24
	v_lshl_add_u32 v26, v11, 11, 0
	v_lshlrev_b32_e32 v27, 2, v11
	s_addc_u32 s5, s1, 0
	s_mov_b32 s14, 0x14000
	v_add_u32_e32 v28, 0x14000, v24
	s_mov_b32 s15, 0x16000
	v_add_u32_e32 v29, 0x16000, v24
	s_mov_b32 s33, 0x18000
	v_add_u32_e32 v30, 0x18000, v24
	s_mov_b32 s34, 0x1a000
	v_add_u32_e32 v31, 0x1a000, v24
	s_mov_b32 s35, 0x1c000
	v_add_u32_e32 v32, 0x1c000, v24
	s_mov_b32 s36, 0x1e000
	v_add_u32_e32 v33, 0x1e000, v24
	v_add_u32_e32 v34, 0x20000, v24
	v_add_u32_e32 v35, 0x22000, v24
	v_add_u32_e32 v36, 0x4000, v8
	s_movk_i32 s37, 0x2400
	s_movk_i32 s44, 0x2000
	s_movk_i32 s45, 0x6000
	s_mov_b32 s46, 0x8000
	s_mov_b32 s47, 0xa000
	s_mov_b32 s48, 0xc000
	s_mov_b32 s49, 0xe000
	s_mov_b32 s50, 0x10000
	s_mov_b32 s51, 0x12000
	v_lshlrev_b32_e32 v4, 2, v4
	s_mov_b64 s[12:13], 0x1400
	s_movk_i32 s52, 0x1000
	s_mov_b32 s53, s2
	s_ashr_i32 s55, s53, 7
	s_bfe_u32 s54, s53, 0x20005
	s_mul_i32 s56, s55, 0x900000
	s_mul_hi_i32 s10, s55, 0x900000
	s_add_u32 s58, s22, s56
	s_addc_u32 s59, s23, s10
	s_lshl_b32 s10, s53, 5
	s_and_b32 s56, s10, 0x3e0
	v_add_u32_e32 v10, s56, v1
	v_mov_b64_e32 v[8:9], s[58:59]
	v_mad_i64_i32 v[8:9], s[58:59], v10, s37, v[8:9]
	s_lshl_b32 s10, s54, 9
	v_lshl_add_u64 v[8:9], v[8:9], 0, s[10:11]
	s_lshl_b32 s10, s55, 2
	s_or_b32 s58, s10, s54
	v_lshl_add_u64 v[8:9], v[8:9], 0, v[4:5]
	s_ashr_i32 s59, s58, 31
	v_add_co_u32_e32 v10, vcc, s52, v8
	s_lshl_b64 s[58:59], s[58:59], 17
	s_nop 0
	v_addc_co_u32_e32 v11, vcc, 0, v9, vcc
	v_lshl_add_u64 v[86:87], v[6:7], 0, s[58:59]
	v_add_co_u32_e32 v20, vcc, s44, v86
	v_lshl_add_u64 v[12:13], v[8:9], 0, s[12:13]
	s_nop 0
	v_addc_co_u32_e32 v21, vcc, 0, v87, vcc
	v_add_co_u32_e32 v38, vcc, s3, v86
	s_waitcnt lgkmcnt(0)
	s_nop 0
	v_addc_co_u32_e32 v39, vcc, 0, v87, vcc
	v_add_co_u32_e32 v42, vcc, s45, v86
	s_nop 0
	v_addc_co_u32_e32 v43, vcc, 0, v87, vcc
	v_add_co_u32_e32 v46, vcc, s46, v86
	s_nop 1
	v_addc_co_u32_e32 v47, vcc, 0, v87, vcc
	v_add_co_u32_e32 v50, vcc, s47, v86
	s_nop 0
	v_addc_co_u32_e32 v51, vcc, 0, v87, vcc
	v_add_co_u32_e32 v54, vcc, s48, v86
	s_nop 0
	v_addc_co_u32_e32 v55, vcc, 0, v87, vcc
	v_add_co_u32_e32 v58, vcc, s49, v86
	s_nop 0
	v_addc_co_u32_e32 v59, vcc, 0, v87, vcc
	v_add_co_u32_e32 v62, vcc, s50, v86
	s_nop 0
	v_addc_co_u32_e32 v63, vcc, 0, v87, vcc
	v_add_co_u32_e32 v66, vcc, s51, v86
	s_mov_b32 s10, -4
	s_nop 0
	v_addc_co_u32_e32 v67, vcc, 0, v87, vcc
	v_add_co_u32_e32 v70, vcc, s14, v86
	v_mov_b32_e32 v37, v26
	s_nop 0
	v_addc_co_u32_e32 v71, vcc, 0, v87, vcc
	v_add_co_u32_e32 v74, vcc, s15, v86
	s_nop 1
	v_addc_co_u32_e32 v75, vcc, 0, v87, vcc
	v_add_co_u32_e32 v78, vcc, s33, v86
	s_nop 0
	s_nop 0
	s_nop 0
	s_nop 0
	s_nop 0
	v_addc_co_u32_e32 v79, vcc, 0, v87, vcc
	v_add_co_u32_e32 v82, vcc, s34, v86
	s_nop 1
	v_addc_co_u32_e32 v83, vcc, 0, v87, vcc
	v_add_co_u32_e32 v88, vcc, s35, v86
	s_nop 0
	v_addc_co_u32_e32 v89, vcc, 0, v87, vcc
	v_add_co_u32_e32 v90, vcc, s36, v86
	s_nop 1
	v_addc_co_u32_e32 v91, vcc, 0, v87, vcc
	s_nop 0
	s_waitcnt vmcnt(0)
	v_mov_b32_e32 v38, v36
	v_mov_b32_e32 v10, 0
	v_mov_b32_e32 v11, v5
	v_mov_b32_e32 v8, 0
	v_mov_b32_e32 v9, v5
	v_mov_b32_e32 v22, 0
	v_mov_b32_e32 v23, v5
	v_mov_b32_e32 v20, 0
	v_mov_b32_e32 v21, v5
	v_mov_b32_e32 v14, 0
	v_mov_b32_e32 v15, v5
	v_mov_b32_e32 v12, 0
	v_mov_b32_e32 v13, v5
	v_mov_b32_e32 v18, 0
	v_mov_b32_e32 v19, v5
	v_mov_b32_e32 v16, 0
	v_mov_b32_e32 v17, v5
	v_add_u32_e32 v124, s56, v27
	s_lshl_b32 s58, s55, 10
	s_ashr_i32 s59, s58, 31
	s_lshl_b64 s[58:59], s[58:59], 2
	s_add_u32 s58, s20, s58
	s_addc_u32 s59, s21, s59
	v_ashrrev_i32_e32 v125, 31, v124
	v_lshl_add_u64 v[126:127], v[124:125], 2, s[58:59]
	global_load_dwordx4 v[120:123], v[126:127], off

; #define LAS __attribute__((address_space(3)))
; __device__ void p_weights_prod(const Args& a, LAS unsigned char* lds) {
;     ...
; #pragma unroll 2
;         for (int c0 = 0; c0 < 128; c0 += 4) {
;             f32x4 w4[4], m4[4];
; #pragma unroll
;             for (int r2 = 0; r2 < 4; ++r2) w4[r2] = *(const LAS f32x4*)(wt + (4 * rq + r2) * 128 + c0);
; #pragma unroll
;             for (int cc = 0; cc < 4; ++cc) m4[cc] = *(const LAS f32x4*)(mmt + (c0 + cc) * 256 + lc0);
; #pragma unroll
;             for (int r2 = 0; r2 < 4; ++r2)
; #pragma unroll
;                 for (int cc = 0; cc < 4; ++cc) acc[r2] += m4[cc] * w4[r2][cc];
;         }
.Lpw_kb:
	ds_read_b128 v[40:43], v38
	ds_read_b128 v[44:47], v38 offset:1024
	ds_read_b128 v[48:51], v38 offset:2048
	ds_read_b128 v[52:55], v38 offset:3072
	ds_read_b128 v[56:59], v37
	ds_read_b128 v[60:63], v37 offset:16
	ds_read_b128 v[64:67], v37 offset:512
	ds_read_b128 v[68:71], v37 offset:528
	ds_read_b128 v[72:75], v37 offset:1024
	ds_read_b128 v[76:79], v37 offset:1040
	ds_read_b128 v[80:83], v37 offset:1536
	ds_read_b128 v[84:87], v37 offset:1552
	ds_read_b128 v[88:91], v38 offset:4096
	ds_read_b128 v[92:95], v38 offset:5120
	ds_read_b128 v[96:99], v38 offset:6144
	ds_read_b128 v[100:103], v38 offset:7168
	s_waitcnt lgkmcnt(11)
	v_pk_fma_f32 v[8:9], v[56:57], v[42:43], v[8:9] op_sel_hi:[0,1,1]
	v_pk_fma_f32 v[10:11], v[56:57], v[40:41], v[10:11] op_sel_hi:[0,1,1]
	s_waitcnt lgkmcnt(9)
	v_pk_fma_f32 v[20:21], v[64:65], v[42:43], v[20:21] op_sel_hi:[0,1,1]
	v_pk_fma_f32 v[22:23], v[64:65], v[40:41], v[22:23] op_sel_hi:[0,1,1]
	s_waitcnt lgkmcnt(7)
	v_pk_fma_f32 v[12:13], v[72:73], v[42:43], v[12:13] op_sel_hi:[0,1,1]
	v_pk_fma_f32 v[14:15], v[72:73], v[40:41], v[14:15] op_sel_hi:[0,1,1]
	s_waitcnt lgkmcnt(5)
	v_pk_fma_f32 v[16:17], v[42:43], v[80:81], v[16:17] op_sel_hi:[1,0,1]
	v_pk_fma_f32 v[18:19], v[40:41], v[80:81], v[18:19] op_sel_hi:[1,0,1]
	v_pk_fma_f32 v[8:9], v[56:57], v[46:47], v[8:9] op_sel:[1,0,0]
	v_pk_fma_f32 v[10:11], v[56:57], v[44:45], v[10:11] op_sel:[1,0,0]
	v_pk_fma_f32 v[20:21], v[64:65], v[46:47], v[20:21] op_sel:[1,0,0]
	v_pk_fma_f32 v[22:23], v[64:65], v[44:45], v[22:23] op_sel:[1,0,0]
	v_pk_fma_f32 v[12:13], v[72:73], v[46:47], v[12:13] op_sel:[1,0,0]
	v_pk_fma_f32 v[14:15], v[72:73], v[44:45], v[14:15] op_sel:[1,0,0]
	v_pk_fma_f32 v[16:17], v[80:81], v[46:47], v[16:17] op_sel:[1,0,0]
	v_pk_fma_f32 v[18:19], v[80:81], v[44:45], v[18:19] op_sel:[1,0,0]
	v_mov_b32_e32 v40, v59
	v_mov_b32_e32 v42, v67
	v_mov_b32_e32 v104, v75
	v_mov_b32_e32 v106, v83
	v_pk_fma_f32 v[10:11], v[58:59], v[48:49], v[10:11] op_sel_hi:[0,1,1]
	v_pk_fma_f32 v[8:9], v[58:59], v[50:51], v[8:9] op_sel_hi:[0,1,1]
	v_pk_fma_f32 v[22:23], v[66:67], v[48:49], v[22:23] op_sel_hi:[0,1,1]
	v_pk_fma_f32 v[20:21], v[66:67], v[50:51], v[20:21] op_sel_hi:[0,1,1]
	v_pk_fma_f32 v[14:15], v[74:75], v[48:49], v[14:15] op_sel_hi:[0,1,1]
	v_pk_fma_f32 v[12:13], v[74:75], v[50:51], v[12:13] op_sel_hi:[0,1,1]
	v_pk_fma_f32 v[18:19], v[82:83], v[48:49], v[18:19] op_sel_hi:[0,1,1]
	v_pk_fma_f32 v[16:17], v[82:83], v[50:51], v[16:17] op_sel_hi:[0,1,1]
	v_pk_fma_f32 v[8:9], v[40:41], v[54:55], v[8:9] op_sel_hi:[0,1,1]
	v_pk_fma_f32 v[10:11], v[40:41], v[52:53], v[10:11] op_sel_hi:[0,1,1]
	v_pk_fma_f32 v[20:21], v[42:43], v[54:55], v[20:21] op_sel_hi:[0,1,1]
	v_pk_fma_f32 v[22:23], v[42:43], v[52:53], v[22:23] op_sel_hi:[0,1,1]
	v_pk_fma_f32 v[12:13], v[104:105], v[54:55], v[12:13] op_sel_hi:[0,1,1]
	v_pk_fma_f32 v[14:15], v[104:105], v[52:53], v[14:15] op_sel_hi:[0,1,1]
	v_pk_fma_f32 v[16:17], v[106:107], v[54:55], v[16:17] op_sel_hi:[0,1,1]
	v_pk_fma_f32 v[18:19], v[106:107], v[52:53], v[18:19] op_sel_hi:[0,1,1]
	s_waitcnt lgkmcnt(3)
	v_pk_fma_f32 v[10:11], v[60:61], v[88:89], v[10:11] op_sel_hi:[0,1,1]
	v_pk_fma_f32 v[8:9], v[60:61], v[90:91], v[8:9] op_sel_hi:[0,1,1]
	v_pk_fma_f32 v[22:23], v[68:69], v[88:89], v[22:23] op_sel_hi:[0,1,1]
	v_pk_fma_f32 v[20:21], v[68:69], v[90:91], v[20:21] op_sel_hi:[0,1,1]
	v_pk_fma_f32 v[14:15], v[76:77], v[88:89], v[14:15] op_sel_hi:[0,1,1]
	v_pk_fma_f32 v[12:13], v[76:77], v[90:91], v[12:13] op_sel_hi:[0,1,1]
	v_pk_fma_f32 v[18:19], v[88:89], v[84:85], v[18:19] op_sel_hi:[1,0,1]
	v_pk_fma_f32 v[16:17], v[90:91], v[84:85], v[16:17] op_sel_hi:[1,0,1]
	s_waitcnt lgkmcnt(2)
	v_pk_fma_f32 v[8:9], v[60:61], v[94:95], v[8:9] op_sel:[1,0,0]
	v_pk_fma_f32 v[10:11], v[60:61], v[92:93], v[10:11] op_sel:[1,0,0]
	v_pk_fma_f32 v[20:21], v[68:69], v[94:95], v[20:21] op_sel:[1,0,0]
	v_pk_fma_f32 v[22:23], v[68:69], v[92:93], v[22:23] op_sel:[1,0,0]
	v_pk_fma_f32 v[12:13], v[76:77], v[94:95], v[12:13] op_sel:[1,0,0]
	v_pk_fma_f32 v[14:15], v[76:77], v[92:93], v[14:15] op_sel:[1,0,0]
	v_pk_fma_f32 v[16:17], v[84:85], v[94:95], v[16:17] op_sel:[1,0,0]
	v_pk_fma_f32 v[18:19], v[84:85], v[92:93], v[18:19] op_sel:[1,0,0]
	s_add_i32 s10, s10, 8
	v_mov_b32_e32 v108, v63
	v_mov_b32_e32 v110, v71
	v_mov_b32_e32 v112, v79
	v_mov_b32_e32 v114, v87
	s_waitcnt lgkmcnt(1)
	v_pk_fma_f32 v[10:11], v[62:63], v[96:97], v[10:11] op_sel_hi:[0,1,1]
	v_pk_fma_f32 v[8:9], v[62:63], v[98:99], v[8:9] op_sel_hi:[0,1,1]
	v_pk_fma_f32 v[22:23], v[70:71], v[96:97], v[22:23] op_sel_hi:[0,1,1]
	v_pk_fma_f32 v[20:21], v[70:71], v[98:99], v[20:21] op_sel_hi:[0,1,1]
	v_pk_fma_f32 v[14:15], v[78:79], v[96:97], v[14:15] op_sel_hi:[0,1,1]
	v_pk_fma_f32 v[12:13], v[78:79], v[98:99], v[12:13] op_sel_hi:[0,1,1]
	v_pk_fma_f32 v[18:19], v[86:87], v[96:97], v[18:19] op_sel_hi:[0,1,1]
	v_pk_fma_f32 v[16:17], v[86:87], v[98:99], v[16:17] op_sel_hi:[0,1,1]
	v_add_u32_e32 v38, 0x2000, v38
	v_add_u32_e32 v37, 32, v37
	s_cmpk_gt_u32 s10, 0x7b
	s_waitcnt lgkmcnt(0)
	v_pk_fma_f32 v[8:9], v[108:109], v[102:103], v[8:9] op_sel_hi:[0,1,1]
	v_pk_fma_f32 v[10:11], v[108:109], v[100:101], v[10:11] op_sel_hi:[0,1,1]
	v_pk_fma_f32 v[20:21], v[110:111], v[102:103], v[20:21] op_sel_hi:[0,1,1]
	v_pk_fma_f32 v[22:23], v[110:111], v[100:101], v[22:23] op_sel_hi:[0,1,1]
	v_pk_fma_f32 v[12:13], v[112:113], v[102:103], v[12:13] op_sel_hi:[0,1,1]
	v_pk_fma_f32 v[14:15], v[112:113], v[100:101], v[14:15] op_sel_hi:[0,1,1]
	v_pk_fma_f32 v[16:17], v[114:115], v[102:103], v[16:17] op_sel_hi:[0,1,1]
	v_pk_fma_f32 v[18:19], v[114:115], v[100:101], v[18:19] op_sel_hi:[0,1,1]
	s_cbranch_scc0 .Lpw_kb
; __device__ void p_weights_prod(const Args& a, LAS unsigned char* lds) {
;     ...
;         const int k0 = kblk * 32 + 4 * rq;
;         const f32x4 gn = *(const f32x4*)(a.norm_gain + l * DM + k0);
; #pragma unroll
;         for (int j = 0; j < 4; ++j) {
;             f16x4 o;
; #pragma unroll
;             for (int r2 = 0; r2 < 4; ++r2) o[r2] = (f16)(acc[r2][j] * gn[r2]);
;             *(f16x4*)(W1T + ((size_t)l * N1 + pn * 256 + rho0 + j) * 1024 + k0) = o;
;         }
;     }
;     __syncthreads();
	v_add_u32_e32 v42, s56, v27
	s_lshl_b32 s56, s55, 10
	s_ashr_i32 s57, s56, 31
	s_lshl_b64 s[56:57], s[56:57], 2
	s_add_u32 s56, s20, s56
	s_addc_u32 s57, s21, s57
	v_ashrrev_i32_e32 v43, 31, v42
	s_lshl_b32 s54, s54, 8
	s_mul_hi_i32 s10, s55, 0xb00
	s_mulk_i32 s55, 0xb00
	s_addk_i32 s54, 0x700
	s_add_u32 s54, s55, s54
	s_addc_u32 s10, s10, 0
	v_mov_b32_e32 v44, v22
	v_mov_b32_e32 v45, v14
	v_mov_b32_e32 v14, v23
	v_mov_b32_e32 v22, v20
	v_mov_b32_e32 v23, v12
	v_mov_b32_e32 v12, v21
	v_lshl_add_u64 v[20:21], v[42:43], 1, s[6:7]
	v_or_b32_e32 v42, s54, v2
	v_mov_b32_e32 v43, s10
	v_lshlrev_b64 v[42:43], 11, v[42:43]
	v_lshl_add_u64 v[46:47], v[20:21], 0, v[42:43]
	v_or_b32_e32 v48, 0x800, v42
	v_mov_b32_e32 v49, v43
	v_or_b32_e32 v50, 0x1000, v42
	v_mov_b32_e32 v51, v43
	v_or_b32_e32 v42, 0x1800, v42
	v_lshl_add_u64 v[48:49], v[20:21], 0, v[48:49]
	v_lshl_add_u64 v[50:51], v[20:21], 0, v[50:51]
	v_lshl_add_u64 v[20:21], v[20:21], 0, v[42:43]
	s_add_i32 s53, s53, s9
	s_cmpk_gt_i32 s53, 0xff
	s_waitcnt vmcnt(0)
	v_mov_b32_e32 v38, v120
	v_mov_b32_e32 v39, v121
	v_mov_b32_e32 v40, v122
	v_mov_b32_e32 v41, v123
	v_mov_b32_e32 v42, v39
	v_mov_b32_e32 v43, v40
	v_fma_mixlo_f16 v37, v10, v38, 0
	v_fma_mixlo_f16 v39, v11, v38, 0
	v_fma_mixlo_f16 v40, v8, v38, 0
	v_fma_mixlo_f16 v38, v9, v38, 0
	v_pk_mul_f32 v[8:9], v[44:45], v[42:43]
	v_fma_mixlo_f16 v18, v18, v41, 0
	v_pk_mul_f32 v[10:11], v[14:15], v[42:43]
	v_pk_mul_f32 v[14:15], v[22:23], v[42:43]
	v_pk_mul_f32 v[12:13], v[12:13], v[42:43]
	v_cvt_pk_f16_f32 v9, v8, v9
	v_fma_mixlo_f16 v19, v19, v41, 0
	v_fma_mixlo_f16 v16, v16, v41, 0
	v_fma_mixlo_f16 v17, v17, v41, 0
	v_cvt_pk_f16_f32 v11, v10, v11
	v_cvt_pk_f16_f32 v14, v14, v15
	v_cvt_pk_f16_f32 v15, v12, v13
	v_pack_b32_f16 v8, v37, v9
	v_alignbit_b32 v9, v18, v9, 16
	v_pack_b32_f16 v10, v39, v11
	v_alignbit_b32 v11, v19, v11, 16
	v_pack_b32_f16 v12, v40, v14
	v_alignbit_b32 v13, v16, v14, 16
	v_pack_b32_f16 v14, v38, v15
	v_alignbit_b32 v15, v17, v15, 16
	global_store_dwordx2 v[46:47], v[8:9], off
	global_store_dwordx2 v[48:49], v[10:11], off
	global_store_dwordx2 v[50:51], v[12:13], off
	global_store_dwordx2 v[20:21], v[14:15], off
	v_add_u32_e32 v0, 0xffffff00, v0
	s_setprio 0
	s_barrier
	s_branch .LBB0_112
